# P1 epilogue fully hand-written: RoPE via DPP row shifts, context K/V cache rows as 16-byte stores
# speedup vs baseline: 1.0924x; 1.0086x over previous
.Lp1e_rope:
	s_nop 7
	s_nop 7
	s_barrier
	v_readlane_b32 s74, v247, 53
	v_readlane_b32 s75, v247, 54
	v_lshlrev_b32_e32 v174, 5, v187
	s_nop 4
	global_load_dwordx4 v[238:241], v174, s[74:75]
	global_load_dwordx4 v[170:173], v174, s[74:75] offset:16
	s_mul_i32 s0, s13, 0x140000
	s_add_u32 s10, s18, s0
	s_addc_u32 s11, s19, 0
	s_lshl_b32 s0, s12, 8
	s_add_u32 s10, s10, s0
	s_addc_u32 s11, s11, 0
	v_lshl_add_u32 v206, v209, 2, v219
	v_mul_u32_u24_e32 v206, 0x1400, v206
	v_lshl_add_u32 v206, v208, 1, v206
	s_lshl_b32 s0, s13, 2
	v_lshrrev_b32_e32 v178, 6, v219
	v_add_u32_e32 v178, s0, v178
	v_and_b32_e32 v178, 31, v178
	v_lshl_add_u32 v178, v178, 6, v220
	v_lshl_add_u32 v179, v209, 8, v220
	v_cndmask_b32_e64 v178, v179, v178, s[36:37]
	v_cndmask_b32_e64 v179, 64, 0, s[36:37]
	v_mul_u32_u24_e32 v207, 5, v179
	s_waitcnt vmcnt(0)
	ds_write_b128 v174, v[238:241] offset:57344
	ds_write_b128 v174, v[170:173] offset:57360
	s_waitcnt lgkmcnt(0)
	s_barrier
	ds_read_b128 v[238:241], v178 offset:57344
	ds_read_b128 v[170:173], v178 offset:61440
	v_add_u32_e32 v178, v178, v179
	ds_read_b128 v[174:177], v178 offset:57344
	ds_read_b128 v[190:193], v178 offset:61440
	v_add_u32_e32 v178, v178, v179
	ds_read_b128 v[248:251], v178 offset:57344
	ds_read_b128 v[252:255], v178 offset:61440
	v_add_u32_e32 v178, v178, v179
	s_waitcnt lgkmcnt(4)
	v_mul_f32_dpp v200, -v114, v170 row_shl:4 row_mask:0xf bank_mask:0x5
	v_mul_f32_dpp v200, v114, v170 row_shr:4 row_mask:0xf bank_mask:0xa
	v_mul_f32_dpp v201, -v82, v171 row_shl:4 row_mask:0xf bank_mask:0x5
	v_mul_f32_dpp v201, v82, v171 row_shr:4 row_mask:0xf bank_mask:0xa
	v_mul_f32_dpp v202, -v98, v172 row_shl:4 row_mask:0xf bank_mask:0x5
	v_mul_f32_dpp v202, v98, v172 row_shr:4 row_mask:0xf bank_mask:0xa
	v_mul_f32_dpp v203, -v66, v173 row_shl:4 row_mask:0xf bank_mask:0x5
	v_mul_f32_dpp v203, v66, v173 row_shr:4 row_mask:0xf bank_mask:0xa
	v_fma_f32 v114, v114, v238, v200
	v_fma_f32 v82, v82, v239, v201
	v_fma_f32 v98, v98, v240, v202
	v_fma_f32 v66, v66, v241, v203
	v_cvt_pk_bf16_f32 v180, v114, v82
	v_cvt_pk_bf16_f32 v181, v98, v66
	global_store_dwordx2 v206, v[180:181], s[10:11]
	s_add_u32 s10, s10, 0x1400
	s_addc_u32 s11, s11, 0
	ds_read_b128 v[238:241], v178 offset:57344
	ds_read_b128 v[170:173], v178 offset:61440
	v_add_u32_e32 v178, v178, v207
	s_waitcnt lgkmcnt(4)
	v_mul_f32_dpp v200, -v115, v190 row_shl:4 row_mask:0xf bank_mask:0x5
	v_mul_f32_dpp v200, v115, v190 row_shr:4 row_mask:0xf bank_mask:0xa
	v_mul_f32_dpp v201, -v83, v191 row_shl:4 row_mask:0xf bank_mask:0x5
	v_mul_f32_dpp v201, v83, v191 row_shr:4 row_mask:0xf bank_mask:0xa
	v_mul_f32_dpp v202, -v99, v192 row_shl:4 row_mask:0xf bank_mask:0x5
	v_mul_f32_dpp v202, v99, v192 row_shr:4 row_mask:0xf bank_mask:0xa
	v_mul_f32_dpp v203, -v67, v193 row_shl:4 row_mask:0xf bank_mask:0x5
	v_mul_f32_dpp v203, v67, v193 row_shr:4 row_mask:0xf bank_mask:0xa
	v_fma_f32 v115, v115, v174, v200
	v_fma_f32 v83, v83, v175, v201
	v_fma_f32 v99, v99, v176, v202
	v_fma_f32 v67, v67, v177, v203
	v_cvt_pk_bf16_f32 v204, v115, v83
	v_cvt_pk_bf16_f32 v205, v99, v67
	global_store_dwordx2 v206, v[204:205], s[10:11]
	s_add_u32 s10, s10, 0x1400
	s_addc_u32 s11, s11, 0
	ds_read_b128 v[174:177], v178 offset:57344
	ds_read_b128 v[190:193], v178 offset:61440
	v_add_u32_e32 v178, v178, v179
	s_waitcnt lgkmcnt(4)
	v_mul_f32_dpp v200, -v116, v252 row_shl:4 row_mask:0xf bank_mask:0x5
	v_mul_f32_dpp v200, v116, v252 row_shr:4 row_mask:0xf bank_mask:0xa
	v_mul_f32_dpp v201, -v84, v253 row_shl:4 row_mask:0xf bank_mask:0x5
	v_mul_f32_dpp v201, v84, v253 row_shr:4 row_mask:0xf bank_mask:0xa
	v_mul_f32_dpp v202, -v100, v254 row_shl:4 row_mask:0xf bank_mask:0x5
	v_mul_f32_dpp v202, v100, v254 row_shr:4 row_mask:0xf bank_mask:0xa
	v_mul_f32_dpp v203, -v68, v255 row_shl:4 row_mask:0xf bank_mask:0x5
	v_mul_f32_dpp v203, v68, v255 row_shr:4 row_mask:0xf bank_mask:0xa
	v_fma_f32 v116, v116, v248, v200
	v_fma_f32 v84, v84, v249, v201
	v_fma_f32 v100, v100, v250, v202
	v_fma_f32 v68, v68, v251, v203
	v_cvt_pk_bf16_f32 v180, v116, v84
	v_cvt_pk_bf16_f32 v181, v100, v68
	global_store_dwordx2 v206, v[180:181], s[10:11]
	s_add_u32 s10, s10, 0x1400
	s_addc_u32 s11, s11, 0
	ds_read_b128 v[248:251], v178 offset:57344
	ds_read_b128 v[252:255], v178 offset:61440
	v_add_u32_e32 v178, v178, v179
	s_waitcnt lgkmcnt(4)
	v_mul_f32_dpp v200, -v117, v170 row_shl:4 row_mask:0xf bank_mask:0x5
	v_mul_f32_dpp v200, v117, v170 row_shr:4 row_mask:0xf bank_mask:0xa
	v_mul_f32_dpp v201, -v85, v171 row_shl:4 row_mask:0xf bank_mask:0x5
	v_mul_f32_dpp v201, v85, v171 row_shr:4 row_mask:0xf bank_mask:0xa
	v_mul_f32_dpp v202, -v101, v172 row_shl:4 row_mask:0xf bank_mask:0x5
	v_mul_f32_dpp v202, v101, v172 row_shr:4 row_mask:0xf bank_mask:0xa
	v_mul_f32_dpp v203, -v69, v173 row_shl:4 row_mask:0xf bank_mask:0x5
	v_mul_f32_dpp v203, v69, v173 row_shr:4 row_mask:0xf bank_mask:0xa
	v_fma_f32 v117, v117, v238, v200
	v_fma_f32 v85, v85, v239, v201
	v_fma_f32 v101, v101, v240, v202
	v_fma_f32 v69, v69, v241, v203
	v_cvt_pk_bf16_f32 v204, v117, v85
	v_cvt_pk_bf16_f32 v205, v101, v69
	global_store_dwordx2 v206, v[204:205], s[10:11]
	s_add_u32 s10, s10, 0x6400
	s_addc_u32 s11, s11, 0
	ds_read_b128 v[238:241], v178 offset:57344
	ds_read_b128 v[170:173], v178 offset:61440
	v_add_u32_e32 v178, v178, v179
	s_waitcnt lgkmcnt(4)
	v_mul_f32_dpp v200, -v118, v190 row_shl:4 row_mask:0xf bank_mask:0x5
	v_mul_f32_dpp v200, v118, v190 row_shr:4 row_mask:0xf bank_mask:0xa
	v_mul_f32_dpp v201, -v86, v191 row_shl:4 row_mask:0xf bank_mask:0x5
	v_mul_f32_dpp v201, v86, v191 row_shr:4 row_mask:0xf bank_mask:0xa
	v_mul_f32_dpp v202, -v102, v192 row_shl:4 row_mask:0xf bank_mask:0x5
	v_mul_f32_dpp v202, v102, v192 row_shr:4 row_mask:0xf bank_mask:0xa
	v_mul_f32_dpp v203, -v70, v193 row_shl:4 row_mask:0xf bank_mask:0x5
	v_mul_f32_dpp v203, v70, v193 row_shr:4 row_mask:0xf bank_mask:0xa
	v_fma_f32 v118, v118, v174, v200
	v_fma_f32 v86, v86, v175, v201
	v_fma_f32 v102, v102, v176, v202
	v_fma_f32 v70, v70, v177, v203
	v_cvt_pk_bf16_f32 v180, v118, v86
	v_cvt_pk_bf16_f32 v181, v102, v70
	global_store_dwordx2 v206, v[180:181], s[10:11]
	s_add_u32 s10, s10, 0x1400
	s_addc_u32 s11, s11, 0
	ds_read_b128 v[174:177], v178 offset:57344
	ds_read_b128 v[190:193], v178 offset:61440
	v_add_u32_e32 v178, v178, v207
	s_waitcnt lgkmcnt(4)
	v_mul_f32_dpp v200, -v119, v252 row_shl:4 row_mask:0xf bank_mask:0x5
	v_mul_f32_dpp v200, v119, v252 row_shr:4 row_mask:0xf bank_mask:0xa
	v_mul_f32_dpp v201, -v87, v253 row_shl:4 row_mask:0xf bank_mask:0x5
	v_mul_f32_dpp v201, v87, v253 row_shr:4 row_mask:0xf bank_mask:0xa
	v_mul_f32_dpp v202, -v103, v254 row_shl:4 row_mask:0xf bank_mask:0x5
	v_mul_f32_dpp v202, v103, v254 row_shr:4 row_mask:0xf bank_mask:0xa
	v_mul_f32_dpp v203, -v71, v255 row_shl:4 row_mask:0xf bank_mask:0x5
	v_mul_f32_dpp v203, v71, v255 row_shr:4 row_mask:0xf bank_mask:0xa
	v_fma_f32 v119, v119, v248, v200
	v_fma_f32 v87, v87, v249, v201
	v_fma_f32 v103, v103, v250, v202
	v_fma_f32 v71, v71, v251, v203
	v_cvt_pk_bf16_f32 v204, v119, v87
	v_cvt_pk_bf16_f32 v205, v103, v71
	global_store_dwordx2 v206, v[204:205], s[10:11]
	s_add_u32 s10, s10, 0x1400
	s_addc_u32 s11, s11, 0
	ds_read_b128 v[248:251], v178 offset:57344
	ds_read_b128 v[252:255], v178 offset:61440
	v_add_u32_e32 v178, v178, v179
	s_waitcnt lgkmcnt(4)
	v_mul_f32_dpp v200, -v120, v170 row_shl:4 row_mask:0xf bank_mask:0x5
	v_mul_f32_dpp v200, v120, v170 row_shr:4 row_mask:0xf bank_mask:0xa
	v_mul_f32_dpp v201, -v88, v171 row_shl:4 row_mask:0xf bank_mask:0x5
	v_mul_f32_dpp v201, v88, v171 row_shr:4 row_mask:0xf bank_mask:0xa
	v_mul_f32_dpp v202, -v104, v172 row_shl:4 row_mask:0xf bank_mask:0x5
	v_mul_f32_dpp v202, v104, v172 row_shr:4 row_mask:0xf bank_mask:0xa
	v_mul_f32_dpp v203, -v72, v173 row_shl:4 row_mask:0xf bank_mask:0x5
	v_mul_f32_dpp v203, v72, v173 row_shr:4 row_mask:0xf bank_mask:0xa
	v_fma_f32 v120, v120, v238, v200
	v_fma_f32 v88, v88, v239, v201
	v_fma_f32 v104, v104, v240, v202
	v_fma_f32 v72, v72, v241, v203
	v_cvt_pk_bf16_f32 v180, v120, v88
	v_cvt_pk_bf16_f32 v181, v104, v72
	global_store_dwordx2 v206, v[180:181], s[10:11]
	s_add_u32 s10, s10, 0x1400
	s_addc_u32 s11, s11, 0
	ds_read_b128 v[238:241], v178 offset:57344
	ds_read_b128 v[170:173], v178 offset:61440
	v_add_u32_e32 v178, v178, v179
	s_waitcnt lgkmcnt(4)
	v_mul_f32_dpp v200, -v121, v190 row_shl:4 row_mask:0xf bank_mask:0x5
	v_mul_f32_dpp v200, v121, v190 row_shr:4 row_mask:0xf bank_mask:0xa
	v_mul_f32_dpp v201, -v89, v191 row_shl:4 row_mask:0xf bank_mask:0x5
	v_mul_f32_dpp v201, v89, v191 row_shr:4 row_mask:0xf bank_mask:0xa
	v_mul_f32_dpp v202, -v105, v192 row_shl:4 row_mask:0xf bank_mask:0x5
	v_mul_f32_dpp v202, v105, v192 row_shr:4 row_mask:0xf bank_mask:0xa
	v_mul_f32_dpp v203, -v73, v193 row_shl:4 row_mask:0xf bank_mask:0x5
	v_mul_f32_dpp v203, v73, v193 row_shr:4 row_mask:0xf bank_mask:0xa
	v_fma_f32 v121, v121, v174, v200
	v_fma_f32 v89, v89, v175, v201
	v_fma_f32 v105, v105, v176, v202
	v_fma_f32 v73, v73, v177, v203
	v_cvt_pk_bf16_f32 v204, v121, v89
	v_cvt_pk_bf16_f32 v205, v105, v73
	global_store_dwordx2 v206, v[204:205], s[10:11]
	s_add_u32 s10, s10, 0x6400
	s_addc_u32 s11, s11, 0
	ds_read_b128 v[174:177], v178 offset:57344
	ds_read_b128 v[190:193], v178 offset:61440
	v_add_u32_e32 v178, v178, v179
	s_waitcnt lgkmcnt(4)
	v_mul_f32_dpp v200, -v122, v252 row_shl:4 row_mask:0xf bank_mask:0x5
	v_mul_f32_dpp v200, v122, v252 row_shr:4 row_mask:0xf bank_mask:0xa
	v_mul_f32_dpp v201, -v90, v253 row_shl:4 row_mask:0xf bank_mask:0x5
	v_mul_f32_dpp v201, v90, v253 row_shr:4 row_mask:0xf bank_mask:0xa
	v_mul_f32_dpp v202, -v106, v254 row_shl:4 row_mask:0xf bank_mask:0x5
	v_mul_f32_dpp v202, v106, v254 row_shr:4 row_mask:0xf bank_mask:0xa
	v_mul_f32_dpp v203, -v74, v255 row_shl:4 row_mask:0xf bank_mask:0x5
	v_mul_f32_dpp v203, v74, v255 row_shr:4 row_mask:0xf bank_mask:0xa
	v_fma_f32 v122, v122, v248, v200
	v_fma_f32 v90, v90, v249, v201
	v_fma_f32 v106, v106, v250, v202
	v_fma_f32 v74, v74, v251, v203
	v_cvt_pk_bf16_f32 v180, v122, v90
	v_cvt_pk_bf16_f32 v181, v106, v74
	global_store_dwordx2 v206, v[180:181], s[10:11]
	s_add_u32 s10, s10, 0x1400
	s_addc_u32 s11, s11, 0
	ds_read_b128 v[248:251], v178 offset:57344
	ds_read_b128 v[252:255], v178 offset:61440
	v_add_u32_e32 v178, v178, v207
	s_waitcnt lgkmcnt(4)
	v_mul_f32_dpp v200, -v123, v170 row_shl:4 row_mask:0xf bank_mask:0x5
	v_mul_f32_dpp v200, v123, v170 row_shr:4 row_mask:0xf bank_mask:0xa
	v_mul_f32_dpp v201, -v91, v171 row_shl:4 row_mask:0xf bank_mask:0x5
	v_mul_f32_dpp v201, v91, v171 row_shr:4 row_mask:0xf bank_mask:0xa
	v_mul_f32_dpp v202, -v107, v172 row_shl:4 row_mask:0xf bank_mask:0x5
	v_mul_f32_dpp v202, v107, v172 row_shr:4 row_mask:0xf bank_mask:0xa
	v_mul_f32_dpp v203, -v75, v173 row_shl:4 row_mask:0xf bank_mask:0x5
	v_mul_f32_dpp v203, v75, v173 row_shr:4 row_mask:0xf bank_mask:0xa
	v_fma_f32 v123, v123, v238, v200
	v_fma_f32 v91, v91, v239, v201
	v_fma_f32 v107, v107, v240, v202
	v_fma_f32 v75, v75, v241, v203
	v_cvt_pk_bf16_f32 v204, v123, v91
	v_cvt_pk_bf16_f32 v205, v107, v75
	global_store_dwordx2 v206, v[204:205], s[10:11]
	s_add_u32 s10, s10, 0x1400
	s_addc_u32 s11, s11, 0
	ds_read_b128 v[238:241], v178 offset:57344
	ds_read_b128 v[170:173], v178 offset:61440
	v_add_u32_e32 v178, v178, v179
	s_waitcnt lgkmcnt(4)
	v_mul_f32_dpp v200, -v124, v190 row_shl:4 row_mask:0xf bank_mask:0x5
	v_mul_f32_dpp v200, v124, v190 row_shr:4 row_mask:0xf bank_mask:0xa
	v_mul_f32_dpp v201, -v92, v191 row_shl:4 row_mask:0xf bank_mask:0x5
	v_mul_f32_dpp v201, v92, v191 row_shr:4 row_mask:0xf bank_mask:0xa
	v_mul_f32_dpp v202, -v108, v192 row_shl:4 row_mask:0xf bank_mask:0x5
	v_mul_f32_dpp v202, v108, v192 row_shr:4 row_mask:0xf bank_mask:0xa
	v_mul_f32_dpp v203, -v76, v193 row_shl:4 row_mask:0xf bank_mask:0x5
	v_mul_f32_dpp v203, v76, v193 row_shr:4 row_mask:0xf bank_mask:0xa
	v_fma_f32 v124, v124, v174, v200
	v_fma_f32 v92, v92, v175, v201
	v_fma_f32 v108, v108, v176, v202
	v_fma_f32 v76, v76, v177, v203
	v_cvt_pk_bf16_f32 v180, v124, v92
	v_cvt_pk_bf16_f32 v181, v108, v76
	global_store_dwordx2 v206, v[180:181], s[10:11]
	s_add_u32 s10, s10, 0x1400
	s_addc_u32 s11, s11, 0
	ds_read_b128 v[174:177], v178 offset:57344
	ds_read_b128 v[190:193], v178 offset:61440
	v_add_u32_e32 v178, v178, v179
	s_waitcnt lgkmcnt(4)
	v_mul_f32_dpp v200, -v125, v252 row_shl:4 row_mask:0xf bank_mask:0x5
	v_mul_f32_dpp v200, v125, v252 row_shr:4 row_mask:0xf bank_mask:0xa
	v_mul_f32_dpp v201, -v93, v253 row_shl:4 row_mask:0xf bank_mask:0x5
	v_mul_f32_dpp v201, v93, v253 row_shr:4 row_mask:0xf bank_mask:0xa
	v_mul_f32_dpp v202, -v109, v254 row_shl:4 row_mask:0xf bank_mask:0x5
	v_mul_f32_dpp v202, v109, v254 row_shr:4 row_mask:0xf bank_mask:0xa
	v_mul_f32_dpp v203, -v77, v255 row_shl:4 row_mask:0xf bank_mask:0x5
	v_mul_f32_dpp v203, v77, v255 row_shr:4 row_mask:0xf bank_mask:0xa
	v_fma_f32 v125, v125, v248, v200
	v_fma_f32 v93, v93, v249, v201
	v_fma_f32 v109, v109, v250, v202
	v_fma_f32 v77, v77, v251, v203
	v_cvt_pk_bf16_f32 v204, v125, v93
	v_cvt_pk_bf16_f32 v205, v109, v77
	global_store_dwordx2 v206, v[204:205], s[10:11]
	s_add_u32 s10, s10, 0x6400
	s_addc_u32 s11, s11, 0
	ds_read_b128 v[248:251], v178 offset:57344
	ds_read_b128 v[252:255], v178 offset:61440
	v_add_u32_e32 v178, v178, v179
	s_waitcnt lgkmcnt(4)
	v_mul_f32_dpp v200, -v126, v170 row_shl:4 row_mask:0xf bank_mask:0x5
	v_mul_f32_dpp v200, v126, v170 row_shr:4 row_mask:0xf bank_mask:0xa
	v_mul_f32_dpp v201, -v94, v171 row_shl:4 row_mask:0xf bank_mask:0x5
	v_mul_f32_dpp v201, v94, v171 row_shr:4 row_mask:0xf bank_mask:0xa
	v_mul_f32_dpp v202, -v110, v172 row_shl:4 row_mask:0xf bank_mask:0x5
	v_mul_f32_dpp v202, v110, v172 row_shr:4 row_mask:0xf bank_mask:0xa
	v_mul_f32_dpp v203, -v78, v173 row_shl:4 row_mask:0xf bank_mask:0x5
	v_mul_f32_dpp v203, v78, v173 row_shr:4 row_mask:0xf bank_mask:0xa
	v_fma_f32 v126, v126, v238, v200
	v_fma_f32 v94, v94, v239, v201
	v_fma_f32 v110, v110, v240, v202
	v_fma_f32 v78, v78, v241, v203
	v_cvt_pk_bf16_f32 v180, v126, v94
	v_cvt_pk_bf16_f32 v181, v110, v78
	global_store_dwordx2 v206, v[180:181], s[10:11]
	s_add_u32 s10, s10, 0x1400
	s_addc_u32 s11, s11, 0
	ds_read_b128 v[238:241], v178 offset:57344
	ds_read_b128 v[170:173], v178 offset:61440
	v_add_u32_e32 v178, v178, v207
	s_waitcnt lgkmcnt(4)
	v_mul_f32_dpp v200, -v127, v190 row_shl:4 row_mask:0xf bank_mask:0x5
	v_mul_f32_dpp v200, v127, v190 row_shr:4 row_mask:0xf bank_mask:0xa
	v_mul_f32_dpp v201, -v95, v191 row_shl:4 row_mask:0xf bank_mask:0x5
	v_mul_f32_dpp v201, v95, v191 row_shr:4 row_mask:0xf bank_mask:0xa
	v_mul_f32_dpp v202, -v111, v192 row_shl:4 row_mask:0xf bank_mask:0x5
	v_mul_f32_dpp v202, v111, v192 row_shr:4 row_mask:0xf bank_mask:0xa
	v_mul_f32_dpp v203, -v79, v193 row_shl:4 row_mask:0xf bank_mask:0x5
	v_mul_f32_dpp v203, v79, v193 row_shr:4 row_mask:0xf bank_mask:0xa
	v_fma_f32 v127, v127, v174, v200
	v_fma_f32 v95, v95, v175, v201
	v_fma_f32 v111, v111, v176, v202
	v_fma_f32 v79, v79, v177, v203
	v_cvt_pk_bf16_f32 v204, v127, v95
	v_cvt_pk_bf16_f32 v205, v111, v79
	global_store_dwordx2 v206, v[204:205], s[10:11]
	s_add_u32 s10, s10, 0x1400
	s_addc_u32 s11, s11, 0
	ds_read_b128 v[174:177], v178 offset:57344
	ds_read_b128 v[190:193], v178 offset:61440
	v_add_u32_e32 v178, v178, v179
	s_waitcnt lgkmcnt(4)
	v_mul_f32_dpp v200, -v128, v252 row_shl:4 row_mask:0xf bank_mask:0x5
	v_mul_f32_dpp v200, v128, v252 row_shr:4 row_mask:0xf bank_mask:0xa
	v_mul_f32_dpp v201, -v96, v253 row_shl:4 row_mask:0xf bank_mask:0x5
	v_mul_f32_dpp v201, v96, v253 row_shr:4 row_mask:0xf bank_mask:0xa
	v_mul_f32_dpp v202, -v112, v254 row_shl:4 row_mask:0xf bank_mask:0x5
	v_mul_f32_dpp v202, v112, v254 row_shr:4 row_mask:0xf bank_mask:0xa
	v_mul_f32_dpp v203, -v80, v255 row_shl:4 row_mask:0xf bank_mask:0x5
	v_mul_f32_dpp v203, v80, v255 row_shr:4 row_mask:0xf bank_mask:0xa
	v_fma_f32 v128, v128, v248, v200
	v_fma_f32 v96, v96, v249, v201
	v_fma_f32 v112, v112, v250, v202
	v_fma_f32 v80, v80, v251, v203
	v_cvt_pk_bf16_f32 v180, v128, v96
	v_cvt_pk_bf16_f32 v181, v112, v80
	global_store_dwordx2 v206, v[180:181], s[10:11]
	s_add_u32 s10, s10, 0x1400
	s_addc_u32 s11, s11, 0
	ds_read_b128 v[248:251], v178 offset:57344
	ds_read_b128 v[252:255], v178 offset:61440
	v_add_u32_e32 v178, v178, v179
	s_waitcnt lgkmcnt(4)
	v_mul_f32_dpp v200, -v129, v170 row_shl:4 row_mask:0xf bank_mask:0x5
	v_mul_f32_dpp v200, v129, v170 row_shr:4 row_mask:0xf bank_mask:0xa
	v_mul_f32_dpp v201, -v97, v171 row_shl:4 row_mask:0xf bank_mask:0x5
	v_mul_f32_dpp v201, v97, v171 row_shr:4 row_mask:0xf bank_mask:0xa
	v_mul_f32_dpp v202, -v113, v172 row_shl:4 row_mask:0xf bank_mask:0x5
	v_mul_f32_dpp v202, v113, v172 row_shr:4 row_mask:0xf bank_mask:0xa
	v_mul_f32_dpp v203, -v81, v173 row_shl:4 row_mask:0xf bank_mask:0x5
	v_mul_f32_dpp v203, v81, v173 row_shr:4 row_mask:0xf bank_mask:0xa
	v_fma_f32 v129, v129, v238, v200
	v_fma_f32 v97, v97, v239, v201
	v_fma_f32 v113, v113, v240, v202
	v_fma_f32 v81, v81, v241, v203
	v_cvt_pk_bf16_f32 v204, v129, v97
	v_cvt_pk_bf16_f32 v205, v113, v81
	global_store_dwordx2 v206, v[204:205], s[10:11]
	s_add_u32 s10, s10, 0x6400
	s_addc_u32 s11, s11, 0
	ds_read_b128 v[238:241], v178 offset:57344
	ds_read_b128 v[170:173], v178 offset:61440
	v_add_u32_e32 v178, v178, v179
	s_waitcnt lgkmcnt(4)
	v_mul_f32_dpp v200, -v50, v190 row_shl:4 row_mask:0xf bank_mask:0x5
	v_mul_f32_dpp v200, v50, v190 row_shr:4 row_mask:0xf bank_mask:0xa
	v_mul_f32_dpp v201, -v18, v191 row_shl:4 row_mask:0xf bank_mask:0x5
	v_mul_f32_dpp v201, v18, v191 row_shr:4 row_mask:0xf bank_mask:0xa
	v_mul_f32_dpp v202, -v34, v192 row_shl:4 row_mask:0xf bank_mask:0x5
	v_mul_f32_dpp v202, v34, v192 row_shr:4 row_mask:0xf bank_mask:0xa
	v_mul_f32_dpp v203, -v2, v193 row_shl:4 row_mask:0xf bank_mask:0x5
	v_mul_f32_dpp v203, v2, v193 row_shr:4 row_mask:0xf bank_mask:0xa
	v_fma_f32 v50, v50, v174, v200
	v_fma_f32 v18, v18, v175, v201
	v_fma_f32 v34, v34, v176, v202
	v_fma_f32 v2, v2, v177, v203
	v_cvt_pk_bf16_f32 v180, v50, v18
	v_cvt_pk_bf16_f32 v181, v34, v2
	global_store_dwordx2 v206, v[180:181], s[10:11]
	s_add_u32 s10, s10, 0x1400
	s_addc_u32 s11, s11, 0
	ds_read_b128 v[174:177], v178 offset:57344
	ds_read_b128 v[190:193], v178 offset:61440
	v_add_u32_e32 v178, v178, v207
	s_waitcnt lgkmcnt(4)
	v_mul_f32_dpp v200, -v51, v252 row_shl:4 row_mask:0xf bank_mask:0x5
	v_mul_f32_dpp v200, v51, v252 row_shr:4 row_mask:0xf bank_mask:0xa
	v_mul_f32_dpp v201, -v19, v253 row_shl:4 row_mask:0xf bank_mask:0x5
	v_mul_f32_dpp v201, v19, v253 row_shr:4 row_mask:0xf bank_mask:0xa
	v_mul_f32_dpp v202, -v35, v254 row_shl:4 row_mask:0xf bank_mask:0x5
	v_mul_f32_dpp v202, v35, v254 row_shr:4 row_mask:0xf bank_mask:0xa
	v_mul_f32_dpp v203, -v3, v255 row_shl:4 row_mask:0xf bank_mask:0x5
	v_mul_f32_dpp v203, v3, v255 row_shr:4 row_mask:0xf bank_mask:0xa
	v_fma_f32 v51, v51, v248, v200
	v_fma_f32 v19, v19, v249, v201
	v_fma_f32 v35, v35, v250, v202
	v_fma_f32 v3, v3, v251, v203
	v_cvt_pk_bf16_f32 v204, v51, v19
	v_cvt_pk_bf16_f32 v205, v35, v3
	global_store_dwordx2 v206, v[204:205], s[10:11]
	s_add_u32 s10, s10, 0x1400
	s_addc_u32 s11, s11, 0
	ds_read_b128 v[248:251], v178 offset:57344
	ds_read_b128 v[252:255], v178 offset:61440
	v_add_u32_e32 v178, v178, v179
	s_waitcnt lgkmcnt(4)
	v_mul_f32_dpp v200, -v52, v170 row_shl:4 row_mask:0xf bank_mask:0x5
	v_mul_f32_dpp v200, v52, v170 row_shr:4 row_mask:0xf bank_mask:0xa
	v_mul_f32_dpp v201, -v20, v171 row_shl:4 row_mask:0xf bank_mask:0x5
	v_mul_f32_dpp v201, v20, v171 row_shr:4 row_mask:0xf bank_mask:0xa
	v_mul_f32_dpp v202, -v36, v172 row_shl:4 row_mask:0xf bank_mask:0x5
	v_mul_f32_dpp v202, v36, v172 row_shr:4 row_mask:0xf bank_mask:0xa
	v_mul_f32_dpp v203, -v4, v173 row_shl:4 row_mask:0xf bank_mask:0x5
	v_mul_f32_dpp v203, v4, v173 row_shr:4 row_mask:0xf bank_mask:0xa
	v_fma_f32 v52, v52, v238, v200
	v_fma_f32 v20, v20, v239, v201
	v_fma_f32 v36, v36, v240, v202
	v_fma_f32 v4, v4, v241, v203
	v_cvt_pk_bf16_f32 v180, v52, v20
	v_cvt_pk_bf16_f32 v181, v36, v4
	global_store_dwordx2 v206, v[180:181], s[10:11]
	s_add_u32 s10, s10, 0x1400
	s_addc_u32 s11, s11, 0
	ds_read_b128 v[238:241], v178 offset:57344
	ds_read_b128 v[170:173], v178 offset:61440
	v_add_u32_e32 v178, v178, v179
	s_waitcnt lgkmcnt(4)
	v_mul_f32_dpp v200, -v53, v190 row_shl:4 row_mask:0xf bank_mask:0x5
	v_mul_f32_dpp v200, v53, v190 row_shr:4 row_mask:0xf bank_mask:0xa
	v_mul_f32_dpp v201, -v21, v191 row_shl:4 row_mask:0xf bank_mask:0x5
	v_mul_f32_dpp v201, v21, v191 row_shr:4 row_mask:0xf bank_mask:0xa
	v_mul_f32_dpp v202, -v37, v192 row_shl:4 row_mask:0xf bank_mask:0x5
	v_mul_f32_dpp v202, v37, v192 row_shr:4 row_mask:0xf bank_mask:0xa
	v_mul_f32_dpp v203, -v5, v193 row_shl:4 row_mask:0xf bank_mask:0x5
	v_mul_f32_dpp v203, v5, v193 row_shr:4 row_mask:0xf bank_mask:0xa
	v_fma_f32 v53, v53, v174, v200
	v_fma_f32 v21, v21, v175, v201
	v_fma_f32 v37, v37, v176, v202
	v_fma_f32 v5, v5, v177, v203
	v_cvt_pk_bf16_f32 v204, v53, v21
	v_cvt_pk_bf16_f32 v205, v37, v5
	global_store_dwordx2 v206, v[204:205], s[10:11]
	s_add_u32 s10, s10, 0x6400
	s_addc_u32 s11, s11, 0
	ds_read_b128 v[174:177], v178 offset:57344
	ds_read_b128 v[190:193], v178 offset:61440
	v_add_u32_e32 v178, v178, v179
	s_waitcnt lgkmcnt(4)
	v_mul_f32_dpp v200, -v54, v252 row_shl:4 row_mask:0xf bank_mask:0x5
	v_mul_f32_dpp v200, v54, v252 row_shr:4 row_mask:0xf bank_mask:0xa
	v_mul_f32_dpp v201, -v22, v253 row_shl:4 row_mask:0xf bank_mask:0x5
	v_mul_f32_dpp v201, v22, v253 row_shr:4 row_mask:0xf bank_mask:0xa
	v_mul_f32_dpp v202, -v38, v254 row_shl:4 row_mask:0xf bank_mask:0x5
	v_mul_f32_dpp v202, v38, v254 row_shr:4 row_mask:0xf bank_mask:0xa
	v_mul_f32_dpp v203, -v6, v255 row_shl:4 row_mask:0xf bank_mask:0x5
	v_mul_f32_dpp v203, v6, v255 row_shr:4 row_mask:0xf bank_mask:0xa
	v_fma_f32 v54, v54, v248, v200
	v_fma_f32 v22, v22, v249, v201
	v_fma_f32 v38, v38, v250, v202
	v_fma_f32 v6, v6, v251, v203
	v_cvt_pk_bf16_f32 v180, v54, v22
	v_cvt_pk_bf16_f32 v181, v38, v6
	global_store_dwordx2 v206, v[180:181], s[10:11]
	s_add_u32 s10, s10, 0x1400
	s_addc_u32 s11, s11, 0
	ds_read_b128 v[248:251], v178 offset:57344
	ds_read_b128 v[252:255], v178 offset:61440
	v_add_u32_e32 v178, v178, v207
	s_waitcnt lgkmcnt(4)
	v_mul_f32_dpp v200, -v55, v170 row_shl:4 row_mask:0xf bank_mask:0x5
	v_mul_f32_dpp v200, v55, v170 row_shr:4 row_mask:0xf bank_mask:0xa
	v_mul_f32_dpp v201, -v23, v171 row_shl:4 row_mask:0xf bank_mask:0x5
	v_mul_f32_dpp v201, v23, v171 row_shr:4 row_mask:0xf bank_mask:0xa
	v_mul_f32_dpp v202, -v39, v172 row_shl:4 row_mask:0xf bank_mask:0x5
	v_mul_f32_dpp v202, v39, v172 row_shr:4 row_mask:0xf bank_mask:0xa
	v_mul_f32_dpp v203, -v7, v173 row_shl:4 row_mask:0xf bank_mask:0x5
	v_mul_f32_dpp v203, v7, v173 row_shr:4 row_mask:0xf bank_mask:0xa
	v_fma_f32 v55, v55, v238, v200
	v_fma_f32 v23, v23, v239, v201
	v_fma_f32 v39, v39, v240, v202
	v_fma_f32 v7, v7, v241, v203
	v_cvt_pk_bf16_f32 v204, v55, v23
	v_cvt_pk_bf16_f32 v205, v39, v7
	global_store_dwordx2 v206, v[204:205], s[10:11]
	s_add_u32 s10, s10, 0x1400
	s_addc_u32 s11, s11, 0
	ds_read_b128 v[238:241], v178 offset:57344
	ds_read_b128 v[170:173], v178 offset:61440
	v_add_u32_e32 v178, v178, v179
	s_waitcnt lgkmcnt(4)
	v_mul_f32_dpp v200, -v56, v190 row_shl:4 row_mask:0xf bank_mask:0x5
	v_mul_f32_dpp v200, v56, v190 row_shr:4 row_mask:0xf bank_mask:0xa
	v_mul_f32_dpp v201, -v24, v191 row_shl:4 row_mask:0xf bank_mask:0x5
	v_mul_f32_dpp v201, v24, v191 row_shr:4 row_mask:0xf bank_mask:0xa
	v_mul_f32_dpp v202, -v40, v192 row_shl:4 row_mask:0xf bank_mask:0x5
	v_mul_f32_dpp v202, v40, v192 row_shr:4 row_mask:0xf bank_mask:0xa
	v_mul_f32_dpp v203, -v8, v193 row_shl:4 row_mask:0xf bank_mask:0x5
	v_mul_f32_dpp v203, v8, v193 row_shr:4 row_mask:0xf bank_mask:0xa
	v_fma_f32 v56, v56, v174, v200
	v_fma_f32 v24, v24, v175, v201
	v_fma_f32 v40, v40, v176, v202
	v_fma_f32 v8, v8, v177, v203
	v_cvt_pk_bf16_f32 v180, v56, v24
	v_cvt_pk_bf16_f32 v181, v40, v8
	global_store_dwordx2 v206, v[180:181], s[10:11]
	s_add_u32 s10, s10, 0x1400
	s_addc_u32 s11, s11, 0
	ds_read_b128 v[174:177], v178 offset:57344
	ds_read_b128 v[190:193], v178 offset:61440
	v_add_u32_e32 v178, v178, v179
	s_waitcnt lgkmcnt(4)
	v_mul_f32_dpp v200, -v57, v252 row_shl:4 row_mask:0xf bank_mask:0x5
	v_mul_f32_dpp v200, v57, v252 row_shr:4 row_mask:0xf bank_mask:0xa
	v_mul_f32_dpp v201, -v25, v253 row_shl:4 row_mask:0xf bank_mask:0x5
	v_mul_f32_dpp v201, v25, v253 row_shr:4 row_mask:0xf bank_mask:0xa
	v_mul_f32_dpp v202, -v41, v254 row_shl:4 row_mask:0xf bank_mask:0x5
	v_mul_f32_dpp v202, v41, v254 row_shr:4 row_mask:0xf bank_mask:0xa
	v_mul_f32_dpp v203, -v9, v255 row_shl:4 row_mask:0xf bank_mask:0x5
	v_mul_f32_dpp v203, v9, v255 row_shr:4 row_mask:0xf bank_mask:0xa
	v_fma_f32 v57, v57, v248, v200
	v_fma_f32 v25, v25, v249, v201
	v_fma_f32 v41, v41, v250, v202
	v_fma_f32 v9, v9, v251, v203
	v_cvt_pk_bf16_f32 v204, v57, v25
	v_cvt_pk_bf16_f32 v205, v41, v9
	global_store_dwordx2 v206, v[204:205], s[10:11]
	s_add_u32 s10, s10, 0x6400
	s_addc_u32 s11, s11, 0
	ds_read_b128 v[248:251], v178 offset:57344
	ds_read_b128 v[252:255], v178 offset:61440
	v_add_u32_e32 v178, v178, v179
	s_waitcnt lgkmcnt(4)
	v_mul_f32_dpp v200, -v58, v170 row_shl:4 row_mask:0xf bank_mask:0x5
	v_mul_f32_dpp v200, v58, v170 row_shr:4 row_mask:0xf bank_mask:0xa
	v_mul_f32_dpp v201, -v26, v171 row_shl:4 row_mask:0xf bank_mask:0x5
	v_mul_f32_dpp v201, v26, v171 row_shr:4 row_mask:0xf bank_mask:0xa
	v_mul_f32_dpp v202, -v42, v172 row_shl:4 row_mask:0xf bank_mask:0x5
	v_mul_f32_dpp v202, v42, v172 row_shr:4 row_mask:0xf bank_mask:0xa
	v_mul_f32_dpp v203, -v10, v173 row_shl:4 row_mask:0xf bank_mask:0x5
	v_mul_f32_dpp v203, v10, v173 row_shr:4 row_mask:0xf bank_mask:0xa
	v_fma_f32 v58, v58, v238, v200
	v_fma_f32 v26, v26, v239, v201
	v_fma_f32 v42, v42, v240, v202
	v_fma_f32 v10, v10, v241, v203
	v_cvt_pk_bf16_f32 v180, v58, v26
	v_cvt_pk_bf16_f32 v181, v42, v10
	global_store_dwordx2 v206, v[180:181], s[10:11]
	s_add_u32 s10, s10, 0x1400
	s_addc_u32 s11, s11, 0
	ds_read_b128 v[238:241], v178 offset:57344
	ds_read_b128 v[170:173], v178 offset:61440
	v_add_u32_e32 v178, v178, v207
	s_waitcnt lgkmcnt(4)
	v_mul_f32_dpp v200, -v59, v190 row_shl:4 row_mask:0xf bank_mask:0x5
	v_mul_f32_dpp v200, v59, v190 row_shr:4 row_mask:0xf bank_mask:0xa
	v_mul_f32_dpp v201, -v27, v191 row_shl:4 row_mask:0xf bank_mask:0x5
	v_mul_f32_dpp v201, v27, v191 row_shr:4 row_mask:0xf bank_mask:0xa
	v_mul_f32_dpp v202, -v43, v192 row_shl:4 row_mask:0xf bank_mask:0x5
	v_mul_f32_dpp v202, v43, v192 row_shr:4 row_mask:0xf bank_mask:0xa
	v_mul_f32_dpp v203, -v11, v193 row_shl:4 row_mask:0xf bank_mask:0x5
	v_mul_f32_dpp v203, v11, v193 row_shr:4 row_mask:0xf bank_mask:0xa
	v_fma_f32 v59, v59, v174, v200
	v_fma_f32 v27, v27, v175, v201
	v_fma_f32 v43, v43, v176, v202
	v_fma_f32 v11, v11, v177, v203
	v_cvt_pk_bf16_f32 v204, v59, v27
	v_cvt_pk_bf16_f32 v205, v43, v11
	global_store_dwordx2 v206, v[204:205], s[10:11]
	s_add_u32 s10, s10, 0x1400
	s_addc_u32 s11, s11, 0
	ds_read_b128 v[174:177], v178 offset:57344
	ds_read_b128 v[190:193], v178 offset:61440
	v_add_u32_e32 v178, v178, v179
	s_waitcnt lgkmcnt(4)
	v_mul_f32_dpp v200, -v60, v252 row_shl:4 row_mask:0xf bank_mask:0x5
	v_mul_f32_dpp v200, v60, v252 row_shr:4 row_mask:0xf bank_mask:0xa
	v_mul_f32_dpp v201, -v28, v253 row_shl:4 row_mask:0xf bank_mask:0x5
	v_mul_f32_dpp v201, v28, v253 row_shr:4 row_mask:0xf bank_mask:0xa
	v_mul_f32_dpp v202, -v44, v254 row_shl:4 row_mask:0xf bank_mask:0x5
	v_mul_f32_dpp v202, v44, v254 row_shr:4 row_mask:0xf bank_mask:0xa
	v_mul_f32_dpp v203, -v12, v255 row_shl:4 row_mask:0xf bank_mask:0x5
	v_mul_f32_dpp v203, v12, v255 row_shr:4 row_mask:0xf bank_mask:0xa
	v_fma_f32 v60, v60, v248, v200
	v_fma_f32 v28, v28, v249, v201
	v_fma_f32 v44, v44, v250, v202
	v_fma_f32 v12, v12, v251, v203
	v_cvt_pk_bf16_f32 v180, v60, v28
	v_cvt_pk_bf16_f32 v181, v44, v12
	global_store_dwordx2 v206, v[180:181], s[10:11]
	s_add_u32 s10, s10, 0x1400
	s_addc_u32 s11, s11, 0
	ds_read_b128 v[248:251], v178 offset:57344
	ds_read_b128 v[252:255], v178 offset:61440
	v_add_u32_e32 v178, v178, v179
	s_waitcnt lgkmcnt(4)
	v_mul_f32_dpp v200, -v61, v170 row_shl:4 row_mask:0xf bank_mask:0x5
	v_mul_f32_dpp v200, v61, v170 row_shr:4 row_mask:0xf bank_mask:0xa
	v_mul_f32_dpp v201, -v29, v171 row_shl:4 row_mask:0xf bank_mask:0x5
	v_mul_f32_dpp v201, v29, v171 row_shr:4 row_mask:0xf bank_mask:0xa
	v_mul_f32_dpp v202, -v45, v172 row_shl:4 row_mask:0xf bank_mask:0x5
	v_mul_f32_dpp v202, v45, v172 row_shr:4 row_mask:0xf bank_mask:0xa
	v_mul_f32_dpp v203, -v13, v173 row_shl:4 row_mask:0xf bank_mask:0x5
	v_mul_f32_dpp v203, v13, v173 row_shr:4 row_mask:0xf bank_mask:0xa
	v_fma_f32 v61, v61, v238, v200
	v_fma_f32 v29, v29, v239, v201
	v_fma_f32 v45, v45, v240, v202
	v_fma_f32 v13, v13, v241, v203
	v_cvt_pk_bf16_f32 v204, v61, v29
	v_cvt_pk_bf16_f32 v205, v45, v13
	global_store_dwordx2 v206, v[204:205], s[10:11]
	s_add_u32 s10, s10, 0x6400
	s_addc_u32 s11, s11, 0
	ds_read_b128 v[238:241], v178 offset:57344
	ds_read_b128 v[170:173], v178 offset:61440
	v_add_u32_e32 v178, v178, v179
	s_waitcnt lgkmcnt(4)
	v_mul_f32_dpp v200, -v62, v190 row_shl:4 row_mask:0xf bank_mask:0x5
	v_mul_f32_dpp v200, v62, v190 row_shr:4 row_mask:0xf bank_mask:0xa
	v_mul_f32_dpp v201, -v30, v191 row_shl:4 row_mask:0xf bank_mask:0x5
	v_mul_f32_dpp v201, v30, v191 row_shr:4 row_mask:0xf bank_mask:0xa
	v_mul_f32_dpp v202, -v46, v192 row_shl:4 row_mask:0xf bank_mask:0x5
	v_mul_f32_dpp v202, v46, v192 row_shr:4 row_mask:0xf bank_mask:0xa
	v_mul_f32_dpp v203, -v14, v193 row_shl:4 row_mask:0xf bank_mask:0x5
	v_mul_f32_dpp v203, v14, v193 row_shr:4 row_mask:0xf bank_mask:0xa
	v_fma_f32 v62, v62, v174, v200
	v_fma_f32 v30, v30, v175, v201
	v_fma_f32 v46, v46, v176, v202
	v_fma_f32 v14, v14, v177, v203
	v_cvt_pk_bf16_f32 v180, v62, v30
	v_cvt_pk_bf16_f32 v181, v46, v14
	global_store_dwordx2 v206, v[180:181], s[10:11]
	s_add_u32 s10, s10, 0x1400
	s_addc_u32 s11, s11, 0
	ds_read_b128 v[174:177], v178 offset:57344
	ds_read_b128 v[190:193], v178 offset:61440
	s_waitcnt lgkmcnt(4)
	v_mul_f32_dpp v200, -v63, v252 row_shl:4 row_mask:0xf bank_mask:0x5
	v_mul_f32_dpp v200, v63, v252 row_shr:4 row_mask:0xf bank_mask:0xa
	v_mul_f32_dpp v201, -v31, v253 row_shl:4 row_mask:0xf bank_mask:0x5
	v_mul_f32_dpp v201, v31, v253 row_shr:4 row_mask:0xf bank_mask:0xa
	v_mul_f32_dpp v202, -v47, v254 row_shl:4 row_mask:0xf bank_mask:0x5
	v_mul_f32_dpp v202, v47, v254 row_shr:4 row_mask:0xf bank_mask:0xa
	v_mul_f32_dpp v203, -v15, v255 row_shl:4 row_mask:0xf bank_mask:0x5
	v_mul_f32_dpp v203, v15, v255 row_shr:4 row_mask:0xf bank_mask:0xa
	v_fma_f32 v63, v63, v248, v200
	v_fma_f32 v31, v31, v249, v201
	v_fma_f32 v47, v47, v250, v202
	v_fma_f32 v15, v15, v251, v203
	v_cvt_pk_bf16_f32 v204, v63, v31
	v_cvt_pk_bf16_f32 v205, v47, v15
	global_store_dwordx2 v206, v[204:205], s[10:11]
	s_add_u32 s10, s10, 0x1400
	s_addc_u32 s11, s11, 0
	s_waitcnt lgkmcnt(2)
	v_mul_f32_dpp v200, -v64, v170 row_shl:4 row_mask:0xf bank_mask:0x5
	v_mul_f32_dpp v200, v64, v170 row_shr:4 row_mask:0xf bank_mask:0xa
	v_mul_f32_dpp v201, -v32, v171 row_shl:4 row_mask:0xf bank_mask:0x5
	v_mul_f32_dpp v201, v32, v171 row_shr:4 row_mask:0xf bank_mask:0xa
	v_mul_f32_dpp v202, -v48, v172 row_shl:4 row_mask:0xf bank_mask:0x5
	v_mul_f32_dpp v202, v48, v172 row_shr:4 row_mask:0xf bank_mask:0xa
	v_mul_f32_dpp v203, -v16, v173 row_shl:4 row_mask:0xf bank_mask:0x5
	v_mul_f32_dpp v203, v16, v173 row_shr:4 row_mask:0xf bank_mask:0xa
	v_fma_f32 v64, v64, v238, v200
	v_fma_f32 v32, v32, v239, v201
	v_fma_f32 v48, v48, v240, v202
	v_fma_f32 v16, v16, v241, v203
	v_cvt_pk_bf16_f32 v180, v64, v32
	v_cvt_pk_bf16_f32 v181, v48, v16
	global_store_dwordx2 v206, v[180:181], s[10:11]
	s_add_u32 s10, s10, 0x1400
	s_addc_u32 s11, s11, 0
	s_waitcnt lgkmcnt(0)
	v_mul_f32_dpp v200, -v65, v190 row_shl:4 row_mask:0xf bank_mask:0x5
	v_mul_f32_dpp v200, v65, v190 row_shr:4 row_mask:0xf bank_mask:0xa
	v_mul_f32_dpp v201, -v33, v191 row_shl:4 row_mask:0xf bank_mask:0x5
	v_mul_f32_dpp v201, v33, v191 row_shr:4 row_mask:0xf bank_mask:0xa
	v_mul_f32_dpp v202, -v49, v192 row_shl:4 row_mask:0xf bank_mask:0x5
	v_mul_f32_dpp v202, v49, v192 row_shr:4 row_mask:0xf bank_mask:0xa
	v_mul_f32_dpp v203, -v17, v193 row_shl:4 row_mask:0xf bank_mask:0x5
	v_mul_f32_dpp v203, v17, v193 row_shr:4 row_mask:0xf bank_mask:0xa
	v_fma_f32 v65, v65, v174, v200
	v_fma_f32 v33, v33, v175, v201
	v_fma_f32 v49, v49, v176, v202
	v_fma_f32 v17, v17, v177, v203
	v_cvt_pk_bf16_f32 v204, v65, v33
	v_cvt_pk_bf16_f32 v205, v49, v17
	global_store_dwordx2 v206, v[204:205], s[10:11]
	s_branch .LBB0_181
.Lp1e_kva:
	s_mul_i32 s44, s0, 0x400000
	s_add_u32 s44, s44, 0x3000000
	s_movk_i32 s46, 0x200
	s_branch .Lp1e_kv
.Lp1e_kvb:
	s_lshr_b32 s44, s0, 1
	s_mul_i32 s44, s44, 0x800000
	s_add_u32 s44, s44, 0x3800000
	s_and_b32 s0, s0, 1
	s_lshl_b32 s0, s0, 9
	s_add_u32 s44, s44, s0
	s_movk_i32 s46, 0x400
.Lp1e_kv:
	s_nop 7
	s_nop 7
	s_lshl_b32 s0, s13, 1
	s_add_i32 s0, s0, s85
	s_lshl_b32 s0, s0, 8
	s_mul_i32 s0, s0, s46
	s_add_u32 s44, s44, s0
	v_readlane_b32 s40, v247, 49
	v_readlane_b32 s41, v247, 50
	s_mul_i32 s47, s46, 5
	s_add_u32 s44, s40, s44
	s_addc_u32 s45, s41, 0
	s_mul_i32 s0, s13, 0x140000
	s_add_u32 s10, s18, s0
	s_addc_u32 s11, s19, 0
	s_lshl_b32 s0, s12, 8
	s_add_u32 s10, s10, s0
	s_addc_u32 s11, s11, 0
	v_lshl_add_u32 v178, v209, 2, v219
	v_mul_lo_u32 v179, v178, s46
	v_lshl_add_u32 v179, v208, 2, v179
	v_mul_u32_u24_e32 v178, 0x1400, v178
	v_lshl_add_u32 v178, v208, 1, v178
	v_cvt_pk_bf16_f32 v180, v114, v82
	v_cvt_pk_bf16_f32 v181, v98, v66
	global_store_dwordx2 v178, v[180:181], s[10:11]
	v_mov_b32_e32 v170, v114
	v_mov_b32_e32 v171, v82
	v_mov_b32_e32 v172, v98
	v_mov_b32_e32 v173, v66
	global_store_dwordx4 v179, v[170:173], s[44:45]
	s_add_u32 s10, s10, 0x1400
	s_addc_u32 s11, s11, 0
	s_add_u32 s44, s44, s46
	s_addc_u32 s45, s45, 0
	v_cvt_pk_bf16_f32 v204, v115, v83
	v_cvt_pk_bf16_f32 v205, v99, v67
	global_store_dwordx2 v178, v[204:205], s[10:11]
	v_mov_b32_e32 v174, v115
	v_mov_b32_e32 v175, v83
	v_mov_b32_e32 v176, v99
	v_mov_b32_e32 v177, v67
	global_store_dwordx4 v179, v[174:177], s[44:45]
	s_add_u32 s10, s10, 0x1400
	s_addc_u32 s11, s11, 0
	s_add_u32 s44, s44, s46
	s_addc_u32 s45, s45, 0
	v_cvt_pk_bf16_f32 v180, v116, v84
	v_cvt_pk_bf16_f32 v181, v100, v68
	global_store_dwordx2 v178, v[180:181], s[10:11]
	v_mov_b32_e32 v190, v116
	v_mov_b32_e32 v191, v84
	v_mov_b32_e32 v192, v100
	v_mov_b32_e32 v193, v68
	global_store_dwordx4 v179, v[190:193], s[44:45]
	s_add_u32 s10, s10, 0x1400
	s_addc_u32 s11, s11, 0
	s_add_u32 s44, s44, s46
	s_addc_u32 s45, s45, 0
	v_cvt_pk_bf16_f32 v204, v117, v85
	v_cvt_pk_bf16_f32 v205, v101, v69
	global_store_dwordx2 v178, v[204:205], s[10:11]
	v_mov_b32_e32 v238, v117
	v_mov_b32_e32 v239, v85
	v_mov_b32_e32 v240, v101
	v_mov_b32_e32 v241, v69
	global_store_dwordx4 v179, v[238:241], s[44:45]
	s_add_u32 s10, s10, 0x6400
	s_addc_u32 s11, s11, 0
	s_add_u32 s44, s44, s47
	s_addc_u32 s45, s45, 0
	v_cvt_pk_bf16_f32 v180, v118, v86
	v_cvt_pk_bf16_f32 v181, v102, v70
	global_store_dwordx2 v178, v[180:181], s[10:11]
	v_mov_b32_e32 v170, v118
	v_mov_b32_e32 v171, v86
	v_mov_b32_e32 v172, v102
	v_mov_b32_e32 v173, v70
	global_store_dwordx4 v179, v[170:173], s[44:45]
	s_add_u32 s10, s10, 0x1400
	s_addc_u32 s11, s11, 0
	s_add_u32 s44, s44, s46
	s_addc_u32 s45, s45, 0
	v_cvt_pk_bf16_f32 v204, v119, v87
	v_cvt_pk_bf16_f32 v205, v103, v71
	global_store_dwordx2 v178, v[204:205], s[10:11]
	v_mov_b32_e32 v174, v119
	v_mov_b32_e32 v175, v87
	v_mov_b32_e32 v176, v103
	v_mov_b32_e32 v177, v71
	global_store_dwordx4 v179, v[174:177], s[44:45]
	s_add_u32 s10, s10, 0x1400
	s_addc_u32 s11, s11, 0
	s_add_u32 s44, s44, s46
	s_addc_u32 s45, s45, 0
	v_cvt_pk_bf16_f32 v180, v120, v88
	v_cvt_pk_bf16_f32 v181, v104, v72
	global_store_dwordx2 v178, v[180:181], s[10:11]
	v_mov_b32_e32 v190, v120
	v_mov_b32_e32 v191, v88
	v_mov_b32_e32 v192, v104
	v_mov_b32_e32 v193, v72
	global_store_dwordx4 v179, v[190:193], s[44:45]
	s_add_u32 s10, s10, 0x1400
	s_addc_u32 s11, s11, 0
	s_add_u32 s44, s44, s46
	s_addc_u32 s45, s45, 0
	v_cvt_pk_bf16_f32 v204, v121, v89
	v_cvt_pk_bf16_f32 v205, v105, v73
	global_store_dwordx2 v178, v[204:205], s[10:11]
	v_mov_b32_e32 v238, v121
	v_mov_b32_e32 v239, v89
	v_mov_b32_e32 v240, v105
	v_mov_b32_e32 v241, v73
	global_store_dwordx4 v179, v[238:241], s[44:45]
	s_add_u32 s10, s10, 0x6400
	s_addc_u32 s11, s11, 0
	s_add_u32 s44, s44, s47
	s_addc_u32 s45, s45, 0
	v_cvt_pk_bf16_f32 v180, v122, v90
	v_cvt_pk_bf16_f32 v181, v106, v74
	global_store_dwordx2 v178, v[180:181], s[10:11]
	v_mov_b32_e32 v170, v122
	v_mov_b32_e32 v171, v90
	v_mov_b32_e32 v172, v106
	v_mov_b32_e32 v173, v74
	global_store_dwordx4 v179, v[170:173], s[44:45]
	s_add_u32 s10, s10, 0x1400
	s_addc_u32 s11, s11, 0
	s_add_u32 s44, s44, s46
	s_addc_u32 s45, s45, 0
	v_cvt_pk_bf16_f32 v204, v123, v91
	v_cvt_pk_bf16_f32 v205, v107, v75
	global_store_dwordx2 v178, v[204:205], s[10:11]
	v_mov_b32_e32 v174, v123
	v_mov_b32_e32 v175, v91
	v_mov_b32_e32 v176, v107
	v_mov_b32_e32 v177, v75
	global_store_dwordx4 v179, v[174:177], s[44:45]
	s_add_u32 s10, s10, 0x1400
	s_addc_u32 s11, s11, 0
	s_add_u32 s44, s44, s46
	s_addc_u32 s45, s45, 0
	v_cvt_pk_bf16_f32 v180, v124, v92
	v_cvt_pk_bf16_f32 v181, v108, v76
	global_store_dwordx2 v178, v[180:181], s[10:11]
	v_mov_b32_e32 v190, v124
	v_mov_b32_e32 v191, v92
	v_mov_b32_e32 v192, v108
	v_mov_b32_e32 v193, v76
	global_store_dwordx4 v179, v[190:193], s[44:45]
	s_add_u32 s10, s10, 0x1400
	s_addc_u32 s11, s11, 0
	s_add_u32 s44, s44, s46
	s_addc_u32 s45, s45, 0
	v_cvt_pk_bf16_f32 v204, v125, v93
	v_cvt_pk_bf16_f32 v205, v109, v77
	global_store_dwordx2 v178, v[204:205], s[10:11]
	v_mov_b32_e32 v238, v125
	v_mov_b32_e32 v239, v93
	v_mov_b32_e32 v240, v109
	v_mov_b32_e32 v241, v77
	global_store_dwordx4 v179, v[238:241], s[44:45]
	s_add_u32 s10, s10, 0x6400
	s_addc_u32 s11, s11, 0
	s_add_u32 s44, s44, s47
	s_addc_u32 s45, s45, 0
	v_cvt_pk_bf16_f32 v180, v126, v94
	v_cvt_pk_bf16_f32 v181, v110, v78
	global_store_dwordx2 v178, v[180:181], s[10:11]
	v_mov_b32_e32 v170, v126
	v_mov_b32_e32 v171, v94
	v_mov_b32_e32 v172, v110
	v_mov_b32_e32 v173, v78
	global_store_dwordx4 v179, v[170:173], s[44:45]
	s_add_u32 s10, s10, 0x1400
	s_addc_u32 s11, s11, 0
	s_add_u32 s44, s44, s46
	s_addc_u32 s45, s45, 0
	v_cvt_pk_bf16_f32 v204, v127, v95
	v_cvt_pk_bf16_f32 v205, v111, v79
	global_store_dwordx2 v178, v[204:205], s[10:11]
	v_mov_b32_e32 v174, v127
	v_mov_b32_e32 v175, v95
	v_mov_b32_e32 v176, v111
	v_mov_b32_e32 v177, v79
	global_store_dwordx4 v179, v[174:177], s[44:45]
	s_add_u32 s10, s10, 0x1400
	s_addc_u32 s11, s11, 0
	s_add_u32 s44, s44, s46
	s_addc_u32 s45, s45, 0
	v_cvt_pk_bf16_f32 v180, v128, v96
	v_cvt_pk_bf16_f32 v181, v112, v80
	global_store_dwordx2 v178, v[180:181], s[10:11]
	v_mov_b32_e32 v190, v128
	v_mov_b32_e32 v191, v96
	v_mov_b32_e32 v192, v112
	v_mov_b32_e32 v193, v80
	global_store_dwordx4 v179, v[190:193], s[44:45]
	s_add_u32 s10, s10, 0x1400
	s_addc_u32 s11, s11, 0
	s_add_u32 s44, s44, s46
	s_addc_u32 s45, s45, 0
	v_cvt_pk_bf16_f32 v204, v129, v97
	v_cvt_pk_bf16_f32 v205, v113, v81
	global_store_dwordx2 v178, v[204:205], s[10:11]
	v_mov_b32_e32 v238, v129
	v_mov_b32_e32 v239, v97
	v_mov_b32_e32 v240, v113
	v_mov_b32_e32 v241, v81
	global_store_dwordx4 v179, v[238:241], s[44:45]
	s_add_u32 s10, s10, 0x6400
	s_addc_u32 s11, s11, 0
	s_add_u32 s44, s44, s47
	s_addc_u32 s45, s45, 0
	v_cvt_pk_bf16_f32 v180, v50, v18
	v_cvt_pk_bf16_f32 v181, v34, v2
	global_store_dwordx2 v178, v[180:181], s[10:11]
	v_mov_b32_e32 v170, v50
	v_mov_b32_e32 v171, v18
	v_mov_b32_e32 v172, v34
	v_mov_b32_e32 v173, v2
	global_store_dwordx4 v179, v[170:173], s[44:45]
	s_add_u32 s10, s10, 0x1400
	s_addc_u32 s11, s11, 0
	s_add_u32 s44, s44, s46
	s_addc_u32 s45, s45, 0
	v_cvt_pk_bf16_f32 v204, v51, v19
	v_cvt_pk_bf16_f32 v205, v35, v3
	global_store_dwordx2 v178, v[204:205], s[10:11]
	v_mov_b32_e32 v174, v51
	v_mov_b32_e32 v175, v19
	v_mov_b32_e32 v176, v35
	v_mov_b32_e32 v177, v3
	global_store_dwordx4 v179, v[174:177], s[44:45]
	s_add_u32 s10, s10, 0x1400
	s_addc_u32 s11, s11, 0
	s_add_u32 s44, s44, s46
	s_addc_u32 s45, s45, 0
	v_cvt_pk_bf16_f32 v180, v52, v20
	v_cvt_pk_bf16_f32 v181, v36, v4
	global_store_dwordx2 v178, v[180:181], s[10:11]
	v_mov_b32_e32 v190, v52
	v_mov_b32_e32 v191, v20
	v_mov_b32_e32 v192, v36
	v_mov_b32_e32 v193, v4
	global_store_dwordx4 v179, v[190:193], s[44:45]
	s_add_u32 s10, s10, 0x1400
	s_addc_u32 s11, s11, 0
	s_add_u32 s44, s44, s46
	s_addc_u32 s45, s45, 0
	v_cvt_pk_bf16_f32 v204, v53, v21
	v_cvt_pk_bf16_f32 v205, v37, v5
	global_store_dwordx2 v178, v[204:205], s[10:11]
	v_mov_b32_e32 v238, v53
	v_mov_b32_e32 v239, v21
	v_mov_b32_e32 v240, v37
	v_mov_b32_e32 v241, v5
	global_store_dwordx4 v179, v[238:241], s[44:45]
	s_add_u32 s10, s10, 0x6400
	s_addc_u32 s11, s11, 0
	s_add_u32 s44, s44, s47
	s_addc_u32 s45, s45, 0
	v_cvt_pk_bf16_f32 v180, v54, v22
	v_cvt_pk_bf16_f32 v181, v38, v6
	global_store_dwordx2 v178, v[180:181], s[10:11]
	v_mov_b32_e32 v170, v54
	v_mov_b32_e32 v171, v22
	v_mov_b32_e32 v172, v38
	v_mov_b32_e32 v173, v6
	global_store_dwordx4 v179, v[170:173], s[44:45]
	s_add_u32 s10, s10, 0x1400
	s_addc_u32 s11, s11, 0
	s_add_u32 s44, s44, s46
	s_addc_u32 s45, s45, 0
	v_cvt_pk_bf16_f32 v204, v55, v23
	v_cvt_pk_bf16_f32 v205, v39, v7
	global_store_dwordx2 v178, v[204:205], s[10:11]
	v_mov_b32_e32 v174, v55
	v_mov_b32_e32 v175, v23
	v_mov_b32_e32 v176, v39
	v_mov_b32_e32 v177, v7
	global_store_dwordx4 v179, v[174:177], s[44:45]
	s_add_u32 s10, s10, 0x1400
	s_addc_u32 s11, s11, 0
	s_add_u32 s44, s44, s46
	s_addc_u32 s45, s45, 0
	v_cvt_pk_bf16_f32 v180, v56, v24
	v_cvt_pk_bf16_f32 v181, v40, v8
	global_store_dwordx2 v178, v[180:181], s[10:11]
	v_mov_b32_e32 v190, v56
	v_mov_b32_e32 v191, v24
	v_mov_b32_e32 v192, v40
	v_mov_b32_e32 v193, v8
	global_store_dwordx4 v179, v[190:193], s[44:45]
	s_add_u32 s10, s10, 0x1400
	s_addc_u32 s11, s11, 0
	s_add_u32 s44, s44, s46
	s_addc_u32 s45, s45, 0
	v_cvt_pk_bf16_f32 v204, v57, v25
	v_cvt_pk_bf16_f32 v205, v41, v9
	global_store_dwordx2 v178, v[204:205], s[10:11]
	v_mov_b32_e32 v238, v57
	v_mov_b32_e32 v239, v25
	v_mov_b32_e32 v240, v41
	v_mov_b32_e32 v241, v9
	global_store_dwordx4 v179, v[238:241], s[44:45]
	s_add_u32 s10, s10, 0x6400
	s_addc_u32 s11, s11, 0
	s_add_u32 s44, s44, s47
	s_addc_u32 s45, s45, 0
	v_cvt_pk_bf16_f32 v180, v58, v26
	v_cvt_pk_bf16_f32 v181, v42, v10
	global_store_dwordx2 v178, v[180:181], s[10:11]
	v_mov_b32_e32 v170, v58
	v_mov_b32_e32 v171, v26
	v_mov_b32_e32 v172, v42
	v_mov_b32_e32 v173, v10
	global_store_dwordx4 v179, v[170:173], s[44:45]
	s_add_u32 s10, s10, 0x1400
	s_addc_u32 s11, s11, 0
	s_add_u32 s44, s44, s46
	s_addc_u32 s45, s45, 0
	v_cvt_pk_bf16_f32 v204, v59, v27
	v_cvt_pk_bf16_f32 v205, v43, v11
	global_store_dwordx2 v178, v[204:205], s[10:11]
	v_mov_b32_e32 v174, v59
	v_mov_b32_e32 v175, v27
	v_mov_b32_e32 v176, v43
	v_mov_b32_e32 v177, v11
	global_store_dwordx4 v179, v[174:177], s[44:45]
	s_add_u32 s10, s10, 0x1400
	s_addc_u32 s11, s11, 0
	s_add_u32 s44, s44, s46
	s_addc_u32 s45, s45, 0
	v_cvt_pk_bf16_f32 v180, v60, v28
	v_cvt_pk_bf16_f32 v181, v44, v12
	global_store_dwordx2 v178, v[180:181], s[10:11]
	v_mov_b32_e32 v190, v60
	v_mov_b32_e32 v191, v28
	v_mov_b32_e32 v192, v44
	v_mov_b32_e32 v193, v12
	global_store_dwordx4 v179, v[190:193], s[44:45]
	s_add_u32 s10, s10, 0x1400
	s_addc_u32 s11, s11, 0
	s_add_u32 s44, s44, s46
	s_addc_u32 s45, s45, 0
	v_cvt_pk_bf16_f32 v204, v61, v29
	v_cvt_pk_bf16_f32 v205, v45, v13
	global_store_dwordx2 v178, v[204:205], s[10:11]
	v_mov_b32_e32 v238, v61
	v_mov_b32_e32 v239, v29
	v_mov_b32_e32 v240, v45
	v_mov_b32_e32 v241, v13
	global_store_dwordx4 v179, v[238:241], s[44:45]
	s_add_u32 s10, s10, 0x6400
	s_addc_u32 s11, s11, 0
	s_add_u32 s44, s44, s47
	s_addc_u32 s45, s45, 0
	v_cvt_pk_bf16_f32 v180, v62, v30
	v_cvt_pk_bf16_f32 v181, v46, v14
	global_store_dwordx2 v178, v[180:181], s[10:11]
	v_mov_b32_e32 v170, v62
	v_mov_b32_e32 v171, v30
	v_mov_b32_e32 v172, v46
	v_mov_b32_e32 v173, v14
	global_store_dwordx4 v179, v[170:173], s[44:45]
	s_add_u32 s10, s10, 0x1400
	s_addc_u32 s11, s11, 0
	s_add_u32 s44, s44, s46
	s_addc_u32 s45, s45, 0
	v_cvt_pk_bf16_f32 v204, v63, v31
	v_cvt_pk_bf16_f32 v205, v47, v15
	global_store_dwordx2 v178, v[204:205], s[10:11]
	v_mov_b32_e32 v174, v63
	v_mov_b32_e32 v175, v31
	v_mov_b32_e32 v176, v47
	v_mov_b32_e32 v177, v15
	global_store_dwordx4 v179, v[174:177], s[44:45]
	s_add_u32 s10, s10, 0x1400
	s_addc_u32 s11, s11, 0
	s_add_u32 s44, s44, s46
	s_addc_u32 s45, s45, 0
	v_cvt_pk_bf16_f32 v180, v64, v32
	v_cvt_pk_bf16_f32 v181, v48, v16
	global_store_dwordx2 v178, v[180:181], s[10:11]
	v_mov_b32_e32 v190, v64
	v_mov_b32_e32 v191, v32
	v_mov_b32_e32 v192, v48
	v_mov_b32_e32 v193, v16
	global_store_dwordx4 v179, v[190:193], s[44:45]
	s_add_u32 s10, s10, 0x1400
	s_addc_u32 s11, s11, 0
	s_add_u32 s44, s44, s46
	s_addc_u32 s45, s45, 0
	v_cvt_pk_bf16_f32 v204, v65, v33
	v_cvt_pk_bf16_f32 v205, v49, v17
	global_store_dwordx2 v178, v[204:205], s[10:11]
	v_mov_b32_e32 v238, v65
	v_mov_b32_e32 v239, v33
	v_mov_b32_e32 v240, v49
	v_mov_b32_e32 v241, v17
	global_store_dwordx4 v179, v[238:241], s[44:45]
	s_branch .LBB0_181
